# XCD grid barrier: non-leader blocks poll the TOPGEN word directly (same generation value) instead of the per-XCD XGEN relay
# speedup vs baseline: 1.0058x; 1.0000x over previous
; DI unsigned xb_ld(unsigned* p)              { return __hip_atomic_load(p, __ATOMIC_RELAXED, __HIP_MEMORY_SCOPE_AGENT); }
; DI unsigned xb_add(unsigned* p, unsigned v) { return __hip_atomic_fetch_add(p, v, __ATOMIC_RELAXED, __HIP_MEMORY_SCOPE_AGENT); }
; #define XB_SPIN(cond, bar) do { unsigned _sp = 0; while (cond) { __builtin_amdgcn_s_sleep(1); \
;     if ((++_sp & 255u) == 0u) { if (xb_ld(&(bar)[XB_TMO])) break; if (_sp > XB_SPIN_CAP) { atomicAdd(&(bar)[XB_TMO], 1u); break; } } } } while (0)
; DI void xcd_barrier(const XcdBarrier& b) {
;     ...
;     const unsigned old = xb_add(&bar[XB_XSUB(b.x)], 1u);
;     const unsigned gen = old / nloc;
;     if (old + 1u == (gen + 1u) * nloc) {
;       __builtin_amdgcn_fence(__ATOMIC_RELEASE, "agent");
;       asm volatile("s_waitcnt vmcnt(0)" ::: "memory");
;       const unsigned og = xb_add(&bar[XB_TOP], 1u);
;       const unsigned tg = og / nx;
;       if (og + 1u == (tg + 1u) * nx) xb_add(&bar[XB_TOPGEN], 1u);
;       else XB_SPIN(xb_ld(&bar[XB_TOPGEN]) == tg, bar);
;       __builtin_amdgcn_fence(__ATOMIC_ACQUIRE, "agent");
;       xb_add(&bar[XB_XGEN(b.x)], 1u);
;       asm volatile("s_waitcnt vmcnt(0)" ::: "memory");
;     } else {
;       XB_SPIN(xb_ld(&bar[XB_XGEN(b.x)]) == gen, bar);
;       __builtin_amdgcn_fence(__ATOMIC_ACQUIRE, "agent");
;       asm volatile("s_waitcnt vmcnt(0)" ::: "memory");
;     }
.LBB0_287:
	s_or_b64 exec, exec, s[8:9]
	v_cvt_f32_u32_e32 v4, v2
	s_waitcnt vmcnt(0)
	v_readfirstlane_b32 s2, v3
	v_sub_u32_e32 v3, 0, v2
	v_rcp_iflag_f32_e32 v4, v4
	v_add_u32_e32 v5, s2, v1
	v_mul_f32_e32 v4, 0x4f7ffffe, v4
	v_cvt_u32_f32_e32 v4, v4
	v_mul_lo_u32 v1, v3, v4
	v_mul_hi_u32 v1, v4, v1
	v_add_u32_e32 v1, v4, v1
	v_mul_hi_u32 v1, v5, v1
	v_mul_lo_u32 v3, v1, v2
	v_sub_u32_e32 v3, v5, v3
	v_add_u32_e32 v4, 1, v1
	v_cmp_ge_u32_e32 vcc, v3, v2
	s_nop 1
	v_cndmask_b32_e32 v1, v1, v4, vcc
	v_sub_u32_e32 v4, v3, v2
	v_cndmask_b32_e32 v3, v3, v4, vcc
	v_add_u32_e32 v4, 1, v1
	v_cmp_ge_u32_e32 vcc, v3, v2
	v_add_u32_e32 v3, 1, v5
	s_nop 0
	v_cndmask_b32_e32 v1, v1, v4, vcc
	v_mul_lo_u32 v4, v2, v1
	v_add_u32_e32 v2, v4, v2
	v_cmp_ne_u32_e32 vcc, v3, v2
	s_and_saveexec_b64 s[6:7], vcc
	s_xor_b64 s[6:7], exec, s[6:7]
	s_cbranch_execz .LBB0_301
	s_waitcnt lgkmcnt(0)
	s_add_u32 s12, s68, 0x3ab03500
	s_addc_u32 s13, s69, 0
	v_mov_b32_e32 v0, 0
	global_load_dword v0, v0, s[12:13] sc1
	s_waitcnt vmcnt(0)
	v_cmp_eq_u32_e32 vcc, v0, v1
	s_and_saveexec_b64 s[8:9], vcc
	s_cbranch_execz .LBB0_300
	s_add_u32 s10, s68, 0x3ab00200
	s_addc_u32 s11, s69, 0
	s_mov_b32 s2, 1
	s_mov_b64 s[14:15], 0
	v_mov_b32_e32 v0, 0
	s_branch .LBB0_291

; DI unsigned xb_ld(unsigned* p)              { return __hip_atomic_load(p, __ATOMIC_RELAXED, __HIP_MEMORY_SCOPE_AGENT); }
; DI unsigned xb_add(unsigned* p, unsigned v) { return __hip_atomic_fetch_add(p, v, __ATOMIC_RELAXED, __HIP_MEMORY_SCOPE_AGENT); }
; #define XB_SPIN(cond, bar) do { unsigned _sp = 0; while (cond) { __builtin_amdgcn_s_sleep(1); \
;     if ((++_sp & 255u) == 0u) { if (xb_ld(&(bar)[XB_TMO])) break; if (_sp > XB_SPIN_CAP) { atomicAdd(&(bar)[XB_TMO], 1u); break; } } } } while (0)
; DI void xcd_barrier(const XcdBarrier& b) {
;     ...
;     const unsigned old = xb_add(&bar[XB_XSUB(b.x)], 1u);
;     const unsigned gen = old / nloc;
;     if (old + 1u == (gen + 1u) * nloc) {
;       __builtin_amdgcn_fence(__ATOMIC_RELEASE, "agent");
;       asm volatile("s_waitcnt vmcnt(0)" ::: "memory");
;       const unsigned og = xb_add(&bar[XB_TOP], 1u);
;       const unsigned tg = og / nx;
;       if (og + 1u == (tg + 1u) * nx) xb_add(&bar[XB_TOPGEN], 1u);
;       else XB_SPIN(xb_ld(&bar[XB_TOPGEN]) == tg, bar);
;       __builtin_amdgcn_fence(__ATOMIC_ACQUIRE, "agent");
;       xb_add(&bar[XB_XGEN(b.x)], 1u);
;       asm volatile("s_waitcnt vmcnt(0)" ::: "memory");
;     } else {
;       XB_SPIN(xb_ld(&bar[XB_XGEN(b.x)]) == gen, bar);
;       __builtin_amdgcn_fence(__ATOMIC_ACQUIRE, "agent");
;       asm volatile("s_waitcnt vmcnt(0)" ::: "memory");
;     }
.LBB0_866:
	s_or_b64 exec, exec, s[10:11]
	v_cvt_f32_u32_e32 v4, v2
	s_waitcnt vmcnt(0)
	v_readfirstlane_b32 s2, v3
	v_sub_u32_e32 v3, 0, v2
	v_rcp_iflag_f32_e32 v4, v4
	v_add_u32_e32 v5, s2, v1
	v_mul_f32_e32 v4, 0x4f7ffffe, v4
	v_cvt_u32_f32_e32 v4, v4
	v_mul_lo_u32 v1, v3, v4
	v_mul_hi_u32 v1, v4, v1
	v_add_u32_e32 v1, v4, v1
	v_mul_hi_u32 v1, v5, v1
	v_mul_lo_u32 v3, v1, v2
	v_sub_u32_e32 v3, v5, v3
	v_add_u32_e32 v4, 1, v1
	v_cmp_ge_u32_e32 vcc, v3, v2
	s_nop 1
	v_cndmask_b32_e32 v1, v1, v4, vcc
	v_sub_u32_e32 v4, v3, v2
	v_cndmask_b32_e32 v3, v3, v4, vcc
	v_add_u32_e32 v4, 1, v1
	v_cmp_ge_u32_e32 vcc, v3, v2
	v_add_u32_e32 v3, 1, v5
	s_nop 0
	v_cndmask_b32_e32 v1, v1, v4, vcc
	v_mul_lo_u32 v4, v2, v1
	v_add_u32_e32 v2, v4, v2
	v_cmp_ne_u32_e32 vcc, v3, v2
	s_and_saveexec_b64 s[8:9], vcc
	s_xor_b64 s[8:9], exec, s[8:9]
	s_cbranch_execz .LBB0_880
	s_waitcnt lgkmcnt(0)
	s_add_u32 s14, s68, 0x3ab03500
	s_addc_u32 s15, s69, 0
	v_mov_b32_e32 v0, 0
	global_load_dword v0, v0, s[14:15] sc1
	s_waitcnt vmcnt(0)
	v_cmp_eq_u32_e32 vcc, v0, v1
	s_and_saveexec_b64 s[10:11], vcc
	s_cbranch_execz .LBB0_879
	s_add_u32 s12, s68, 0x3ab00200
	s_addc_u32 s13, s69, 0
	s_mov_b32 s2, 1
	s_mov_b64 s[16:17], 0
	v_mov_b32_e32 v0, 0
	s_branch .LBB0_870

; DI unsigned xb_ld(unsigned* p)              { return __hip_atomic_load(p, __ATOMIC_RELAXED, __HIP_MEMORY_SCOPE_AGENT); }
; DI unsigned xb_add(unsigned* p, unsigned v) { return __hip_atomic_fetch_add(p, v, __ATOMIC_RELAXED, __HIP_MEMORY_SCOPE_AGENT); }
; #define XB_SPIN(cond, bar) do { unsigned _sp = 0; while (cond) { __builtin_amdgcn_s_sleep(1); \
;     if ((++_sp & 255u) == 0u) { if (xb_ld(&(bar)[XB_TMO])) break; if (_sp > XB_SPIN_CAP) { atomicAdd(&(bar)[XB_TMO], 1u); break; } } } } while (0)
; DI void xcd_barrier(const XcdBarrier& b) {
;     ...
;     const unsigned old = xb_add(&bar[XB_XSUB(b.x)], 1u);
;     const unsigned gen = old / nloc;
;     if (old + 1u == (gen + 1u) * nloc) {
;       __builtin_amdgcn_fence(__ATOMIC_RELEASE, "agent");
;       asm volatile("s_waitcnt vmcnt(0)" ::: "memory");
;       const unsigned og = xb_add(&bar[XB_TOP], 1u);
;       const unsigned tg = og / nx;
;       if (og + 1u == (tg + 1u) * nx) xb_add(&bar[XB_TOPGEN], 1u);
;       else XB_SPIN(xb_ld(&bar[XB_TOPGEN]) == tg, bar);
;       __builtin_amdgcn_fence(__ATOMIC_ACQUIRE, "agent");
;       xb_add(&bar[XB_XGEN(b.x)], 1u);
;       asm volatile("s_waitcnt vmcnt(0)" ::: "memory");
;     } else {
;       XB_SPIN(xb_ld(&bar[XB_XGEN(b.x)]) == gen, bar);
;       __builtin_amdgcn_fence(__ATOMIC_ACQUIRE, "agent");
;       asm volatile("s_waitcnt vmcnt(0)" ::: "memory");
;     }
.LBB0_1146:
	s_or_b64 exec, exec, s[6:7]
	v_cvt_f32_u32_e32 v4, v2
	s_waitcnt vmcnt(0)
	v_readfirstlane_b32 s4, v3
	v_sub_u32_e32 v3, 0, v2
	v_rcp_iflag_f32_e32 v4, v4
	v_add_u32_e32 v5, s4, v1
	v_mul_f32_e32 v4, 0x4f7ffffe, v4
	v_cvt_u32_f32_e32 v4, v4
	v_mul_lo_u32 v1, v3, v4
	v_mul_hi_u32 v1, v4, v1
	v_add_u32_e32 v1, v4, v1
	v_mul_hi_u32 v1, v5, v1
	v_mul_lo_u32 v3, v1, v2
	v_sub_u32_e32 v3, v5, v3
	v_add_u32_e32 v4, 1, v1
	v_cmp_ge_u32_e32 vcc, v3, v2
	s_nop 1
	v_cndmask_b32_e32 v1, v1, v4, vcc
	v_sub_u32_e32 v4, v3, v2
	v_cndmask_b32_e32 v3, v3, v4, vcc
	v_add_u32_e32 v4, 1, v1
	v_cmp_ge_u32_e32 vcc, v3, v2
	v_add_u32_e32 v3, 1, v5
	s_nop 0
	v_cndmask_b32_e32 v1, v1, v4, vcc
	v_mul_lo_u32 v4, v2, v1
	v_add_u32_e32 v2, v4, v2
	v_cmp_ne_u32_e32 vcc, v3, v2
	s_and_saveexec_b64 s[4:5], vcc
	s_xor_b64 s[4:5], exec, s[4:5]
	s_cbranch_execz .LBB0_1160
	s_waitcnt lgkmcnt(0)
	s_add_u32 s10, s68, 0x3ab03500
	s_addc_u32 s11, s69, 0
	v_mov_b32_e32 v0, 0
	global_load_dword v0, v0, s[10:11] sc1
	s_waitcnt vmcnt(0)
	v_cmp_eq_u32_e32 vcc, v0, v1
	s_and_saveexec_b64 s[6:7], vcc
	s_cbranch_execz .LBB0_1159
	s_add_u32 s8, s68, 0x3ab00200
	s_addc_u32 s9, s69, 0
	s_mov_b32 s26, 1
	s_mov_b64 s[12:13], 0
	v_mov_b32_e32 v0, 0
	s_branch .LBB0_1150
